# M1/M3 item loops: wave 0 no longer stalls on the work-queue atomic's return at the top of each item (result only needed at the item's end)
# speedup vs baseline: 1.0078x; 1.0078x over previous
; __device__ __forceinline__ int lane_id() { int t; asm volatile("v_mbcnt_lo_u32_b32 %0, -1, 0\n\tv_mbcnt_hi_u32_b32 %0, -1, %0" : "=&v"(t)); return t; }
; __global__ void __launch_bounds__(512, 2) fwd_megakernel(Params P) {
;     ...
;           while (it < N_ATT_ITEMS + N_LA_ITEMS) {
;               unsigned nx = 0; if (wv == 0 && lane_id() == 0) nx = __hip_atomic_fetch_add(ctr, 1u, __ATOMIC_RELAXED, __HIP_MEMORY_SCOPE_AGENT);
;               if (it < N_ATT_ITEMS) attn_item(P, l, lds, it, wv); else la_state_item(P, l, lds, it - N_ATT_ITEMS, wv);
;               __syncthreads(); if (wv == 0 && lane_id() == 0) xb_words.w = nx + (unsigned)G; __syncthreads(); it = (int)xb_words.w; } }
.LBB0_303:
	v_mbcnt_lo_u32_b32 v0, -1, 0
	v_mbcnt_hi_u32_b32 v0, -1, v0
	v_mov_b32_e32 v115, 0
	v_cmp_eq_u32_e32 vcc, 0, v0
	s_and_saveexec_b64 s[0:1], vcc
	s_cbranch_execz .LBB0_307
	s_mov_b64 s[14:15], exec
	v_mbcnt_lo_u32_b32 v0, s14, 0
	v_mbcnt_hi_u32_b32 v0, s15, v0
	v_cmp_eq_u32_e32 vcc, 0, v0
	s_and_saveexec_b64 s[8:9], vcc
	s_cbranch_execz .LBB0_306
	s_bcnt1_i32_b64 s14, s[14:15]
	v_mov_b32_e32 v115, s14
	global_atomic_add v115, v9, v115, s[4:5] sc0
.LBB0_306:
	s_or_b64 exec, exec, s[8:9]
.LBB0_307:
	s_or_b64 exec, exec, s[0:1]
	s_cmpk_gt_i32 s20, 0x21f
	s_mov_b64 s[0:1], -1
	s_cbranch_scc0 .LBB0_302

; __device__ __forceinline__ int lane_id() { int t; asm volatile("v_mbcnt_lo_u32_b32 %0, -1, 0\n\tv_mbcnt_hi_u32_b32 %0, -1, %0" : "=&v"(t)); return t; }
; __global__ void __launch_bounds__(512, 2) fwd_megakernel(Params P) {
;     ...
;           while (it < N_LA_ITEMS) {
;               unsigned nx = 0; if (wv == 0 && lane_id() == 0) nx = __hip_atomic_fetch_add(ctr, 1u, __ATOMIC_RELAXED, __HIP_MEMORY_SCOPE_AGENT);
;               la_out_item(P, l, lds, it, wv);
;               __syncthreads(); if (wv == 0 && lane_id() == 0) xb_words.w = nx + (unsigned)G; __syncthreads(); it = (int)xb_words.w; } }
.LBB0_510:
	s_and_b64 vcc, exec, s[86:87]
	v_mov_b32_e32 v84, 0
	s_cbranch_vccnz .LBB0_516
	v_mbcnt_lo_u32_b32 v0, -1, 0
	v_mbcnt_hi_u32_b32 v0, -1, v0
	v_mov_b32_e32 v84, 0
	v_cmp_eq_u32_e32 vcc, 0, v0
	s_and_saveexec_b64 s[0:1], vcc
	s_cbranch_execz .LBB0_515
	s_mov_b64 s[14:15], exec
	v_mbcnt_lo_u32_b32 v0, s14, 0
	v_mbcnt_hi_u32_b32 v0, s15, v0
	v_cmp_eq_u32_e32 vcc, 0, v0
	s_and_saveexec_b64 s[8:9], vcc
	s_cbranch_execz .LBB0_514
	s_bcnt1_i32_b64 s14, s[14:15]
	v_mov_b32_e32 v84, s14
	global_atomic_add v84, v9, v84, s[4:5] sc0
